# P3->P4 and P4->P5 seams: skip L2 write-back and cache invalidate when every blockIdx%8 group sits on one XCC (run-time check, else full barrier)
# baseline (speedup 1.0000x reference)
; #define LAS __attribute__((address_space(3)))
; __device__ __forceinline__ int lane_id() { return (int)__builtin_amdgcn_mbcnt_hi(~0u, __builtin_amdgcn_mbcnt_lo(~0u, 0u)); }
; __device__ __forceinline__ unsigned xb_add(unsigned* p, unsigned v) { return __hip_atomic_fetch_add(p, v, __ATOMIC_RELAXED, __HIP_MEMORY_SCOPE_AGENT); }
; __device__ __forceinline__ unsigned xb_xcc_id() { return (unsigned)__builtin_amdgcn_s_getreg((3 << 11) | 20) & 0xFu; }
; __device__ __forceinline__ XcdBarrier xcd_barrier_post(unsigned* bar, volatile LAS unsigned* st, int wave) {
;     XcdBarrier b; b.bar = bar; b.x = xb_xcc_id(); b.st = st; b.wave = wave;
;     if (wave == 0 && lane_id() == 0) (void)xb_add(&bar[XB_XCNT(b.x)], 1u);
;     return b;
; }
; __global__ void __launch_bounds__(NTHR, 2) fwd_kernel(Args args) {
;     extern __shared__ __attribute__((aligned(16))) unsigned char lds_raw[];
;     LAS unsigned char* lds = (LAS unsigned char*)lds_raw;
;     cg::grid_group grid = cg::this_grid();
;     const int tid = threadIdx.x, lane0 = tid & 63, wave = __builtin_amdgcn_readfirstlane(tid >> 6);
;     const int G0 = gridDim.x, bx0 = blockIdx.x;
;     ...
;     unsigned char* ws = args.ws;
;     Ptrs P;
;     KArgs kargs = (KArgs)__builtin_amdgcn_kernarg_segment_ptr();
;     P.wave = wave;
;     const int lo = args.ph_lo, hi = args.ph_hi;
;     volatile LAS unsigned* bst = (volatile LAS unsigned*)(lds + LDS_BYTES - 64);
;     if (tid < 2) bst[tid] = 0u;
;     __syncthreads();
;     const XcdBarrier xbar = xcd_barrier_post((unsigned*)(ws + OFF_BAR), bst, wave);
_Z10fwd_kernel4Args:
	s_load_dwordx4 s[4:7], s[0:1], 0xa0
	s_mov_b32 s79, s2
	s_load_dwordx2 s[2:3], s[0:1], 0xb0
	v_and_b32_e32 v16, 0x3ff, v0
	v_cmp_gt_u32_e32 vcc, 2, v16
	s_waitcnt lgkmcnt(0)
	v_writelane_b32 v254, s4, 0
	s_nop 1
	v_writelane_b32 v254, s5, 1
	v_writelane_b32 v254, s6, 2
	v_writelane_b32 v254, s7, 3
	v_writelane_b32 v254, s2, 4
	s_nop 1
	v_writelane_b32 v254, s3, 5
	s_load_dword s2, s[0:1], 0xb8
	s_waitcnt lgkmcnt(0)
	v_writelane_b32 v254, s2, 6
	s_add_u32 s2, s0, 0xb0
	v_writelane_b32 v254, s0, 7
	s_addc_u32 s3, s1, 0
	s_nop 0
	v_writelane_b32 v254, s1, 8
	v_readfirstlane_b32 s0, v16
	s_nop 1
	v_writelane_b32 v254, s0, 9
	s_and_saveexec_b64 s[0:1], vcc
	v_lshl_add_u32 v1, v16, 2, 0
	v_add_u32_e32 v1, 0x23fc0, v1
	v_mov_b32_e32 v2, 0
	ds_write_b32 v1, v2
	s_or_b64 exec, exec, s[0:1]
	v_readlane_b32 s4, v254, 0
	v_readlane_b32 s5, v254, 1
	s_add_u32 s0, s4, 0x33170000
	s_addc_u32 s1, s5, 0
	v_readlane_b32 s6, v254, 2
	v_readlane_b32 s7, v254, 3
	v_writelane_b32 v254, s0, 10
	s_waitcnt lgkmcnt(0)
	s_barrier
	v_writelane_b32 v254, s1, 11
	s_getreg_b32 s0, hwreg(HW_REG_XCC_ID, 0, 4)
	s_and_b32 s0, s0, 15
	v_writelane_b32 v254, s0, 12
	s_nop 0
	v_readlane_b32 s4, v254, 9
	s_cmp_lt_u32 s4, 64
	s_cselect_b64 s[0:1], -1, 0
	v_writelane_b32 v254, s0, 13
	s_cmp_gt_u32 s4, 63
	s_nop 0
	v_writelane_b32 v254, s1, 14
	s_cbranch_scc1 .LBB0_7
	v_mbcnt_lo_u32_b32 v1, -1, 0
	v_mbcnt_hi_u32_b32 v1, -1, v1
	v_cmp_eq_u32_e32 vcc, 0, v1
	s_and_saveexec_b64 s[0:1], vcc
	s_cbranch_execz .LBB0_6
	s_mov_b64 s[4:5], exec
	v_mbcnt_lo_u32_b32 v1, s4, 0
	v_mbcnt_hi_u32_b32 v1, s5, v1
	v_cmp_eq_u32_e32 vcc, 0, v1
	s_and_b64 s[6:7], exec, vcc
	s_mov_b64 exec, s[6:7]
	s_cbranch_execz .LBB0_6
	v_readlane_b32 s6, v254, 12
	s_bcnt1_i32_b64 s4, s[4:5]
	s_lshl_b32 s6, s6, 8
	v_mov_b32_e32 v2, s4
	v_readlane_b32 s4, v254, 10
	v_mov_b32_e32 v1, s6
	v_readlane_b32 s5, v254, 11
	s_nop 4
	global_atomic_add v1, v2, s[4:5] offset:1024
	v_readlane_b32 s90, v254, 12
	s_and_b32 s91, s79, 7
	s_lshl_b32 s91, s91, 2
	s_nop 3
	s_add_i32 s93, s90, 1
	s_sub_i32 s90, 16, s90
	v_mov_b32_e32 v4, s91
	v_mov_b32_e32 v5, s93
	v_mov_b32_e32 v6, s90
	global_atomic_umax v4, v5, s[4:5] offset:64
	global_atomic_umax v4, v6, s[4:5] offset:128

; __device__ __forceinline__ int opq(int v) { asm volatile("" : "+v"(v)); return v; }
; __device__ __forceinline__ int lane_id() { return (int)__builtin_amdgcn_mbcnt_hi(~0u, __builtin_amdgcn_mbcnt_lo(~0u, 0u)); }
; template <class Epi, class Sched, bool ALIGN_EPI, bool F8 = false>
; __device__ __forceinline__ void gemm_phase(LAS unsigned char* lds, const Gemm g, const Sched& S, const Epi& E) {
;     const int wid = __builtin_amdgcn_readfirstlane(g.wave), tid = opq((wid << 6) | lane_id()), lane = tid & 63, wr = wid >> 2, wc = wid & 3, fr = lane & 15, fq = lane >> 4;
;     const int K = g.K, nt = K / BK;
;     unsigned voffA[2], voffB[2];
; #pragma unroll
;     for (int i = 0; i < 2; ++i) { int R, C; stage_rc(tid * 16 + i * 8192, R, C); const int Rb = (R & ~31) + perm32(R & 31);
;         voffA[i] = (unsigned)(R * g.lda + C) * 2u; voffB[i] = (unsigned)(Rb * g.ldb + C) * 2u; }
;     const unsigned kstep = (unsigned)(BK * 2);
;     const unsigned hstepA = (unsigned)HALF * g.lda * 2u, hstepB = (unsigned)HALF * g.ldb * 2u;
;     const unsigned tstepA = 2u * hstepA, tstepB = 2u * hstepB;
;     const unsigned ldsw = (unsigned)wid * 1024u;
;     const unsigned lds_w32 = (unsigned)__builtin_amdgcn_readfirstlane((int)((unsigned)(uintptr_t)lds + ldsw));
;     constexpr int KOFF = F8 ? 16 : 1024;
;     const int aoff = lds_byte(wr * 64 + fr, F8 ? fq * 16 : fq * 8), boff = lds_byte(wc * 32 + fr, F8 ? fq * 16 : fq * 8);
;     ...
;     Unit cur, nxt; int ui = 0;
;     if (!S.next(0, cur)) return;
;     f32x4 acc[2][2][4][2];
; #pragma unroll
;     for (int a = 0; a < 2; ++a)
; #pragma unroll
;         for (int b = 0; b < 2; ++b)
; #pragma unroll
;             for (int m = 0; m < 4; ++m)
; #pragma unroll
;                 for (int n = 0; n < 2; ++n) acc[a][b][m][n] = (f32x4){0.f, 0.f, 0.f, 0.f};
;     v8i_t At[4], B0[2], B1[2];
;     unsigned cA = (unsigned)cur.pm * tstepA + (unsigned)cur.z * (unsigned)g.zA, cB = (unsigned)cur.pn * tstepB + (unsigned)cur.z * (unsigned)g.zB;
;     __amdgpu_buffer_rsrc_t rsA = __builtin_amdgcn_make_buffer_rsrc((void*)g.A, 0, 0x7fffffff, 0x00020000), rsB = __builtin_amdgcn_make_buffer_rsrc((void*)g.Bt, 0, 0x7fffffff, 0x00020000); (void)rsA; (void)rsB;
;     PG8_STAGE_B(PG8_SB(0, 0), cB); PG8_STAGE_B(PG8_SB(0, 1), cB + hstepB); PG8_STAGE_A(PG8_SA(0, 0), cA); PG8_STAGE_A(PG8_SA(0, 1), cA + hstepA);
;     if (wr == 1) PG8_BAR;
.LBB0_573:
	v_readlane_b32 s90, v254, 10
	v_readlane_b32 s91, v254, 11
	v_readlane_b32 s93, v254, 4
	v_mov_b32_e32 v0, 0
	s_nop 4
	global_load_dwordx4 v[2:5], v0, s[90:91] offset:64 sc1
	global_load_dwordx4 v[6:9], v0, s[90:91] offset:80 sc1
	global_load_dwordx4 v[10:13], v0, s[90:91] offset:128 sc1
	global_load_dwordx4 v[14:17], v0, s[90:91] offset:144 sc1
	s_waitcnt vmcnt(0)
	v_add_u32_e32 v2, v2, v10
	v_add_u32_e32 v3, v3, v11
	v_add_u32_e32 v4, v4, v12
	v_add_u32_e32 v5, v5, v13
	v_add_u32_e32 v6, v6, v14
	v_add_u32_e32 v7, v7, v15
	v_add_u32_e32 v8, v8, v16
	v_add_u32_e32 v9, v9, v17
	v_xor_b32_e32 v2, 17, v2
	v_xor_b32_e32 v3, 17, v3
	v_xor_b32_e32 v4, 17, v4
	v_xor_b32_e32 v5, 17, v5
	v_xor_b32_e32 v6, 17, v6
	v_xor_b32_e32 v7, 17, v7
	v_xor_b32_e32 v8, 17, v8
	v_xor_b32_e32 v9, 17, v9
	v_or3_b32 v2, v2, v3, v4
	v_or3_b32 v5, v5, v6, v7
	v_or3_b32 v2, v2, v5, v8
	v_or_b32_e32 v2, v2, v9
	s_nop 1
	v_readfirstlane_b32 s92, v2
	s_nop 3
	s_cmp_eq_u32 s92, 0
	s_cselect_b32 s92, 1, 0
	s_cmp_eq_u32 s93, 0x100
	s_cselect_b32 s92, s92, 0
	v_readlane_b32 s0, v254, 0
	v_readlane_b32 s2, v254, 2
	s_cmp_lt_i32 s2, 2
	v_readlane_b32 s1, v254, 1
	s_cselect_b64 s[22:23], -1, 0
	s_and_b64 s[0:1], s[22:23], s[44:45]
	s_andn2_b64 vcc, exec, s[0:1]
	v_readlane_b32 s3, v254, 3
	s_cbranch_vccnz .LBB0_630
	v_readlane_b32 s0, v254, 7
	v_readlane_b32 s1, v254, 8
	s_load_dwordx2 s[48:49], s[0:1], 0xa0
	v_mbcnt_lo_u32_b32 v0, -1, 0
	v_readlane_b32 s0, v254, 4
	v_mbcnt_hi_u32_b32 v149, -1, v0
	s_mov_b32 s18, s0
	s_waitcnt lgkmcnt(0)
	s_add_u32 s34, s48, 0xef00000
	s_addc_u32 s35, s49, 0
	s_add_u32 s44, s48, 0x1ff00000
	s_addc_u32 s45, s49, 0
	s_mov_b32 s19, s79
	v_mov_b32_e32 v0, v149
	s_add_u32 s46, s48, 0x32f00000
	v_readlane_b32 s0, v254, 15
	s_addc_u32 s47, s49, 0
	s_cmpk_gt_i32 s19, 0xa7f
	v_lshl_or_b32 v253, s0, 6, v149
	v_mov_b32_e32 v0, v253
	v_readlane_b32 s1, v254, 5
	s_cbranch_scc1 .LBB0_598
	v_bfe_i32 v3, v0, 27, 1
	v_lshlrev_b32_e32 v1, 4, v0
	v_lshrrev_b32_e32 v3, 22, v3
	v_add_u32_e32 v3, v1, v3
	v_and_b32_e32 v3, 0xfffffc00, v3
	v_sub_u32_e32 v3, v1, v3
	v_ashrrev_i32_e32 v2, 31, v0
	v_lshrrev_b32_e32 v4, 4, v3
	v_lshrrev_b32_e32 v2, 26, v2
	v_bitop3_b32 v4, v4, v3, 32 bitop3:0x6c
	v_ashrrev_i32_e32 v3, 31, v3
	v_add_u32_e32 v2, v0, v2
	v_lshrrev_b32_e32 v3, 26, v3
	v_ashrrev_i32_e32 v2, 6, v2
	v_add_u32_e32 v3, v4, v3
	v_lshlrev_b32_e32 v5, 3, v2
	v_ashrrev_i32_e32 v3, 6, v3
	v_and_b32_e32 v5, -16, v5
	v_mul_i32_i24_e32 v6, 64, v3
	v_add_u32_e32 v5, v3, v5
	v_sub_u32_e32 v4, v4, v6
	v_mov_b32_e32 v6, 1
	v_lshlrev_b32_e32 v2, 5, v2
	v_ashrrev_i16_sdwa v4, v6, sext(v4) dst_sel:DWORD dst_unused:UNUSED_PAD src0_sel:DWORD src1_sel:BYTE_0
	v_lshlrev_b32_e32 v7, 1, v5
	v_lshrrev_b32_e32 v8, 2, v5
	v_and_b32_e32 v3, 3, v3
	s_mov_b32 s0, 0x1fffe0
	v_and_b32_e32 v2, 32, v2
	v_bfe_i32 v4, v4, 0, 16
	v_and_b32_e32 v7, 24, v7
	v_and_b32_e32 v8, 4, v8
	v_and_or_b32 v3, v5, s0, v3
	v_or3_b32 v3, v3, v8, v7
	v_add_lshl_u32 v2, v2, v4, 1
	v_add_u32_e32 v1, 0x2000, v1
	v_lshl_add_u32 v252, v5, 11, v2
	v_lshl_add_u32 v158, v3, 11, v2
	v_ashrrev_i32_e32 v2, 31, v1
	v_lshrrev_b32_e32 v2, 22, v2
	v_add_u32_e32 v2, v1, v2
	v_ashrrev_i32_e32 v2, 10, v2
	v_mul_i32_i24_e32 v3, 0x400, v2
	v_sub_u32_e32 v1, v1, v3
	v_lshrrev_b32_e32 v3, 4, v1
	v_bitop3_b32 v1, v3, v1, 32 bitop3:0x6c
	v_ashrrev_i32_e32 v4, 31, v1
	v_lshrrev_b32_e32 v4, 26, v4
	v_lshlrev_b32_e32 v3, 3, v2
	v_add_u32_e32 v4, v1, v4
	v_and_b32_e32 v3, -16, v3
	v_ashrrev_i32_e32 v5, 6, v4
	v_add_u32_e32 v3, v5, v3
	v_and_b32_e32 v5, 3, v5
	v_readlane_b32 s1, v254, 15
	v_and_or_b32 v5, v3, s0, v5
	s_ashr_i32 s0, s1, 2
	s_lshl_b32 s5, s1, 10
	s_add_u32 s24, s48, 0x4a00000
	s_addc_u32 s8, s49, 0
	s_ashr_i32 s33, s19, 31
	s_lshr_b32 s1, s33, 29
	s_add_i32 s1, s19, s1
	s_ashr_i32 s2, s1, 3
	s_and_b32 s1, s1, -8
	s_sub_i32 s1, s19, s1
	s_cmp_lt_i32 s1, 0
	s_movk_i32 s36, 0x151
	s_cselect_b32 s3, s36, 0x150
	s_mul_i32 s1, s3, s1
	s_add_i32 s1, s1, s2
	s_ashr_i32 s2, s1, 31
	s_lshr_b32 s2, s2, 24
	v_and_b32_e32 v4, 0xc0, v4
	s_add_i32 s2, s1, s2
	v_sub_u32_e32 v1, v1, v4
	s_ashr_i32 s2, s2, 8
	v_lshlrev_b32_e32 v2, 5, v2
	v_ashrrev_i16_sdwa v1, v6, sext(v1) dst_sel:DWORD dst_unused:UNUSED_PAD src0_sel:DWORD src1_sel:BYTE_0
	s_lshl_b32 s4, s2, 2
	v_and_b32_e32 v2, 32, v2
	v_bfe_i32 v1, v1, 0, 16
	s_sub_i32 s3, 42, s4
	s_lshl_b32 s2, s2, 8
	v_lshlrev_b32_e32 v4, 1, v3
	v_lshrrev_b32_e32 v6, 2, v3
	v_add_lshl_u32 v1, v2, v1, 1
	s_min_u32 s6, s3, 4
	s_sub_i32 s7, s1, s2
	v_and_b32_e32 v4, 24, v4
	v_and_b32_e32 v6, 4, v6
	v_lshl_add_u32 v159, v3, 11, v1
	s_sext_i32_i16 s1, s7
	v_cvt_f32_ubyte0_e32 v3, s6
	v_or3_b32 v4, v5, v6, v4
	v_cvt_f32_i32_e32 v2, s1
	v_rcp_iflag_f32_e32 v5, v3
	v_lshl_add_u32 v160, v4, 11, v1
	s_ashr_i32 s1, s1, 30
	s_or_b32 s1, s1, 1
	v_mul_f32_e32 v1, v2, v5
	v_trunc_f32_e32 v1, v1
	v_fma_f32 v2, -v1, v3, v2
	v_cvt_i32_f32_e32 v1, v1
	v_cmp_ge_f32_e64 s[2:3], |v2|, v3
	s_and_b64 s[2:3], s[2:3], exec
	s_cselect_b32 s1, s1, 0
	v_readfirstlane_b32 s2, v1
	s_add_i32 s1, s2, s1
	s_mul_i32 s2, s1, s6
	s_sub_i32 s2, s7, s2
	s_sext_i32_i16 s2, s2
	s_add_i32 s37, s5, 0
	s_add_i32 s4, s4, s2
	s_add_i32 s38, s37, 0x10000
	s_lshl_b32 s7, s4, 19
	s_and_b32 s29, s49, 0xffff
	s_mov_b32 s31, 0x20000
	s_brev_b32 s30, -2
	s_mov_b32 s28, s48
	s_mov_b32 m0, s38
	s_add_i32 s39, s37, 0x12000
	buffer_load_dwordx4 v158, s[28:31], s7 offen lds
	s_mov_b32 m0, s39
	s_add_i32 s40, s37, 0x14000
	buffer_load_dwordx4 v160, s[28:31], s7 offen lds
	s_or_b32 s2, s7, 0x40000
	s_mov_b32 m0, s40
	s_add_i32 s41, s37, 0x16000
	buffer_load_dwordx4 v158, s[28:31], s2 offen lds
	s_mov_b32 m0, s41
	s_and_b32 s25, s8, 0xffff
	s_lshl_b32 s6, s1, 19
	buffer_load_dwordx4 v160, s[28:31], s2 offen lds
	s_mov_b32 s8, s24
	s_mov_b32 s9, s25
	s_mov_b32 s10, s30
	s_mov_b32 s11, s31
	s_mov_b32 m0, s37
	s_add_i32 s42, s37, 0x2000
	buffer_load_dwordx4 v252, s[8:11], s6 offen lds
	s_mov_b32 m0, s42
	s_add_i32 s43, s37, 0x4000
	buffer_load_dwordx4 v159, s[8:11], s6 offen lds
	s_or_b32 s2, s6, 0x40000
	s_mov_b32 m0, s43
	s_add_i32 s54, s37, 0x6000
	buffer_load_dwordx4 v252, s[8:11], s2 offen lds
	s_mov_b32 m0, s54
	s_cmp_eq_u32 s0, 1
	buffer_load_dwordx4 v159, s[8:11], s2 offen lds
	s_mov_b32 s26, s30
	s_cselect_b64 s[50:51], -1, 0
	s_cmp_lg_u32 s0, 1
	s_mov_b32 s27, s31
	s_cbranch_scc1 .LBB0_577
	s_barrier

; __device__ __forceinline__ unsigned xb_ld(unsigned* p)              { return __hip_atomic_load(p, __ATOMIC_RELAXED, __HIP_MEMORY_SCOPE_AGENT); }
; #define XB_SPIN(cond, bar) do { unsigned _sp = 0; while (cond) { __builtin_amdgcn_s_sleep(1); \
;     if ((++_sp & 255u) == 0u) { if (xb_ld(&(bar)[XB_TMO])) break; if (_sp > XB_SPIN_CAP) { atomicAdd(&(bar)[XB_TMO], 1u); break; } } } } while (0)
; __device__ __forceinline__ void xcd_barrier(const XcdBarrier& b) {
;     ...
;             XB_SPIN(xb_ld(&bar[XB_XGEN(b.x)]) == gen, bar);
;             __builtin_amdgcn_fence(__ATOMIC_ACQUIRE, "agent");
;             asm volatile("s_waitcnt vmcnt(0)" ::: "memory");
.LBB0_1200:
	s_or_b64 exec, exec, s[2:3]
	s_waitcnt vmcnt(0) lgkmcnt(0)
	s_cmp_lg_u32 s92, 0
	s_cbranch_scc1 .Lxl_l0p3_1
	buffer_inv sc1

; __device__ __forceinline__ unsigned xb_ld(unsigned* p)              { return __hip_atomic_load(p, __ATOMIC_RELAXED, __HIP_MEMORY_SCOPE_AGENT); }
; __device__ __forceinline__ unsigned xb_add(unsigned* p, unsigned v) { return __hip_atomic_fetch_add(p, v, __ATOMIC_RELAXED, __HIP_MEMORY_SCOPE_AGENT); }
; #define XB_SPIN(cond, bar) do { unsigned _sp = 0; while (cond) { __builtin_amdgcn_s_sleep(1); \
;     if ((++_sp & 255u) == 0u) { if (xb_ld(&(bar)[XB_TMO])) break; if (_sp > XB_SPIN_CAP) { atomicAdd(&(bar)[XB_TMO], 1u); break; } } } } while (0)
; __device__ __forceinline__ void xcd_barrier(const XcdBarrier& b) {
;     ...
;         const unsigned old = xb_add(&bar[XB_XSUB(b.x)], 1u);
;         const unsigned gen = old / nloc;
;         if (old + 1u == (gen + 1u) * nloc) {
;             __builtin_amdgcn_fence(__ATOMIC_RELEASE, "agent");
;             asm volatile("s_waitcnt vmcnt(0)" ::: "memory");
;             const unsigned og = xb_add(&bar[XB_TOP], 1u);
;             const unsigned tg = og / nx;
;             if (og + 1u == (tg + 1u) * nx) xb_add(&bar[XB_TOPGEN], 1u);
;             else XB_SPIN(xb_ld(&bar[XB_TOPGEN]) == tg, bar);
.LBB0_1201:
	s_andn2_saveexec_b64 s[0:1], s[0:1]
	s_cbranch_execz .LBB0_1217
	v_mov_b32_e32 v1, s48
	v_add_co_u32_e32 v2, vcc, 0x3000, v1
	v_mov_b32_e32 v1, s49
	s_cmp_lg_u32 s92, 0
	s_cbranch_scc1 .Lxl_l0p3_0
	buffer_wbl2 sc1
.Lxl_l0p3_0:
	s_waitcnt vmcnt(0)
	v_addc_co_u32_e32 v3, vcc, 0, v1, vcc
	v_mov_b32_e32 v1, 1
	flat_atomic_add v1, v[2:3], v1 offset:1024 sc0
	v_cvt_f32_u32_e32 v2, v0
	v_sub_u32_e32 v3, 0, v0
	s_add_u32 s0, s21, 0x2400
	s_addc_u32 s1, s20, 0
	v_rcp_iflag_f32_e32 v2, v2
	s_mov_b64 s[4:5], -1
	v_mul_f32_e32 v2, 0x4f7ffffe, v2
	v_cvt_u32_f32_e32 v2, v2
	v_mul_lo_u32 v3, v3, v2
	v_mul_hi_u32 v3, v2, v3
	v_add_u32_e32 v2, v2, v3
	s_waitcnt vmcnt(0) lgkmcnt(0)
	v_mul_hi_u32 v2, v1, v2
	v_mul_lo_u32 v4, v2, v0
	v_add_u32_e32 v3, 1, v1
	v_sub_u32_e32 v1, v1, v4
	v_add_u32_e32 v5, 1, v2
	v_cmp_ge_u32_e32 vcc, v1, v0
	v_sub_u32_e32 v4, v1, v0
	s_nop 0
	v_cndmask_b32_e32 v2, v2, v5, vcc
	v_cndmask_b32_e32 v1, v1, v4, vcc
	v_add_u32_e32 v4, 1, v2
	v_cmp_ge_u32_e32 vcc, v1, v0
	s_nop 1
	v_cndmask_b32_e32 v2, v2, v4, vcc
	v_mad_u64_u32 v[0:1], s[2:3], v0, v2, v[0:1]
	v_cmp_ne_u32_e32 vcc, v3, v0
	v_mov_b64_e32 v[0:1], s[0:1]
	s_and_saveexec_b64 s[2:3], vcc
	s_cbranch_execz .LBB0_1214
	v_mov_b64_e32 v[0:1], s[0:1]
	flat_load_dword v0, v[0:1] sc1
	s_mov_b64 s[8:9], 0
	s_waitcnt vmcnt(0) lgkmcnt(0)
	v_cmp_eq_u32_e32 vcc, v0, v2
	s_and_saveexec_b64 s[6:7], vcc
	s_cbranch_execz .LBB0_1213
	s_add_u32 s4, s48, 0x200
	s_addc_u32 s5, s49, 0
	s_mov_b32 s22, 1
	s_branch .LBB0_1206

; __device__ __forceinline__ unsigned xb_add(unsigned* p, unsigned v) { return __hip_atomic_fetch_add(p, v, __ATOMIC_RELAXED, __HIP_MEMORY_SCOPE_AGENT); }
; __device__ __forceinline__ void xcd_barrier(const XcdBarrier& b) {
;     ...
;             __builtin_amdgcn_fence(__ATOMIC_ACQUIRE, "agent");
;             xb_add(&bar[XB_XGEN(b.x)], 1u);
;             asm volatile("s_waitcnt vmcnt(0)" ::: "memory");
.LBB0_1216:
	s_or_b64 exec, exec, s[0:1]
	v_mov_b32_e32 v0, s21
	v_add_co_u32_e32 v0, vcc, 0x2000, v0
	v_mov_b32_e32 v1, s20
	s_nop 0
	v_addc_co_u32_e32 v1, vcc, 0, v1, vcc
	v_mov_b32_e32 v2, 1
	s_waitcnt vmcnt(0) lgkmcnt(0)
	s_cmp_lg_u32 s92, 0
	s_cbranch_scc1 .Lxl_l0p3_2
	buffer_inv sc1
.Lxl_l0p3_2:
	s_waitcnt vmcnt(0)
.LBB0_1217:
	s_or_b64 exec, exec, s[46:47]

; __device__ __forceinline__ unsigned xb_ld(unsigned* p)              { return __hip_atomic_load(p, __ATOMIC_RELAXED, __HIP_MEMORY_SCOPE_AGENT); }
; #define XB_SPIN(cond, bar) do { unsigned _sp = 0; while (cond) { __builtin_amdgcn_s_sleep(1); \
;     if ((++_sp & 255u) == 0u) { if (xb_ld(&(bar)[XB_TMO])) break; if (_sp > XB_SPIN_CAP) { atomicAdd(&(bar)[XB_TMO], 1u); break; } } } } while (0)
; __device__ __forceinline__ void xcd_barrier(const XcdBarrier& b) {
;     ...
;             asm volatile("s_waitcnt vmcnt(0)" ::: "memory");
;         } else {
;             XB_SPIN(xb_ld(&bar[XB_XGEN(b.x)]) == gen, bar);
;             __builtin_amdgcn_fence(__ATOMIC_ACQUIRE, "agent");
;             asm volatile("s_waitcnt vmcnt(0)" ::: "memory");
;         }
;     }
.Lxl_l0p4_2:
	s_waitcnt vmcnt(0)
.LBB0_1332:
	s_or_b64 exec, exec, s[46:47]

; __device__ __forceinline__ unsigned xb_ld(unsigned* p)              { return __hip_atomic_load(p, __ATOMIC_RELAXED, __HIP_MEMORY_SCOPE_AGENT); }
; #define XB_SPIN(cond, bar) do { unsigned _sp = 0; while (cond) { __builtin_amdgcn_s_sleep(1); \
;     if ((++_sp & 255u) == 0u) { if (xb_ld(&(bar)[XB_TMO])) break; if (_sp > XB_SPIN_CAP) { atomicAdd(&(bar)[XB_TMO], 1u); break; } } } } while (0)
; __device__ __forceinline__ void xcd_barrier(const XcdBarrier& b) {
;     ...
;             asm volatile("s_waitcnt vmcnt(0)" ::: "memory");
;         } else {
;             XB_SPIN(xb_ld(&bar[XB_XGEN(b.x)]) == gen, bar);
;             __builtin_amdgcn_fence(__ATOMIC_ACQUIRE, "agent");
;             asm volatile("s_waitcnt vmcnt(0)" ::: "memory");
;         }
;     }
.Lxl_l1p3_2:
	s_waitcnt vmcnt(0)
.LBB0_2069:
	s_or_b64 exec, exec, s[46:47]

; __device__ __forceinline__ unsigned xb_ld(unsigned* p)              { return __hip_atomic_load(p, __ATOMIC_RELAXED, __HIP_MEMORY_SCOPE_AGENT); }
; #define XB_SPIN(cond, bar) do { unsigned _sp = 0; while (cond) { __builtin_amdgcn_s_sleep(1); \
;     if ((++_sp & 255u) == 0u) { if (xb_ld(&(bar)[XB_TMO])) break; if (_sp > XB_SPIN_CAP) { atomicAdd(&(bar)[XB_TMO], 1u); break; } } } } while (0)
; __device__ __forceinline__ void xcd_barrier(const XcdBarrier& b) {
;     ...
;             asm volatile("s_waitcnt vmcnt(0)" ::: "memory");
;         } else {
;             XB_SPIN(xb_ld(&bar[XB_XGEN(b.x)]) == gen, bar);
;             __builtin_amdgcn_fence(__ATOMIC_ACQUIRE, "agent");
;             asm volatile("s_waitcnt vmcnt(0)" ::: "memory");
;         }
;     }
.Lxl_l1p4_2:
	s_waitcnt vmcnt(0)
.LBB0_2184:
	s_or_b64 exec, exec, s[46:47]
